# v35: phase-2 gate MFMAs read the cached gate weights and bias splat from their home registers (no per-item copies in and out: 21 fewer moves per item)
# baseline (speedup 1.0000x reference)
; #define LAS __attribute__((address_space(3)))
; __device__ __forceinline__ void phase_gla_pre(const Params& P, LAS unsigned char* lds, bool dry) {
;     ...
;         bf16x8 bhi = (bf16x8){0, 0, 0, 0, 0, 0, 0, 0}, blo = bhi;
;         if (g < 2) { f32x4 w0, w1;
; #pragma unroll
;             for (int j = 0; j < 4; ++j) { w0[j] = P.w_gate_up[(8 * g + j) * 512 + h * 128 + 16 * w + fr]; w1[j] = P.w_gate_up[(8 * g + 4 + j) * 512 + h * 128 + 16 * w + fr]; }
;             split8(w0, w1, bhi, blo); }
;         const float bg = P.b_gate_up[h * 128 + 16 * w + fr];
;         __syncthreads();
;         float run = 0.f;
; #pragma unroll
;         for (int tt = 0; tt < 4; ++tt) {
;             bf16x8 ahi = (bf16x8){0, 0, 0, 0, 0, 0, 0, 0}, alo = ahi;
;             if (g < 2) { const f32x4 l0 = *(const LAS f32x4*)(Llr + (16 * tt + fr) * 16 + 8 * g), l1 = *(const LAS f32x4*)(Llr + (16 * tt + fr) * 16 + 8 * g + 4); split8(l0, l1, ahi, alo); }
;             f32x4 acc = (f32x4){bg, bg, bg, bg};
;             acc = __builtin_amdgcn_mfma_f32_16x16x32_bf16(alo, bhi, acc, 0, 0, 0); acc = __builtin_amdgcn_mfma_f32_16x16x32_bf16(ahi, blo, acc, 0, 0, 0); acc = __builtin_amdgcn_mfma_f32_16x16x32_bf16(ahi, bhi, acc, 0, 0, 0);
;             float pr[4];
; #pragma unroll
;             for (int r = 0; r < 4; ++r) { const float lg = acc[r]; const float ls = fminf(lg, 0.f) - __logf(1.0f + __expf(-fabsf(lg))); pr[r] = ls * (1.0f / 16.0f) + (r ? pr[r - 1] : 0.f); }
.Lp2_hoisted:
.Lp2_join:
	s_waitcnt lgkmcnt(0)
	s_barrier
	v_mov_b32_e32 v100, 0
	v_mov_b32_e32 v101, 0
	v_mov_b32_e32 v102, 0
	v_mov_b32_e32 v103, 0
	v_mov_b32_e32 v104, 0
	v_mov_b32_e32 v105, 0
	v_mov_b32_e32 v106, 0
	v_mov_b32_e32 v107, 0
	s_and_saveexec_b64 s[36:37], s[6:7]
	s_cbranch_execz .LBB0_486
	ds_read_b128 v[30:33], v96
	ds_read_b128 v[34:37], v96 offset:16
	s_waitcnt lgkmcnt(1)
	v_cvt_pk_bf16_f32 v104, v30, v31
	v_lshlrev_b32_e32 v132, 16, v104
	v_and_b32_e32 v133, 0xffff0000, v104
	v_pk_add_f32 v[30:31], v[30:31], v[132:133] neg_lo:[0,1] neg_hi:[0,1]
	v_cvt_pk_bf16_f32 v105, v32, v33
	v_lshlrev_b32_e32 v134, 16, v105
	v_and_b32_e32 v135, 0xffff0000, v105
	v_pk_add_f32 v[32:33], v[32:33], v[134:135] neg_lo:[0,1] neg_hi:[0,1]
	s_waitcnt lgkmcnt(0)
	v_cvt_pk_bf16_f32 v106, v34, v35
	v_lshlrev_b32_e32 v136, 16, v106
	v_and_b32_e32 v137, 0xffff0000, v106
	v_pk_add_f32 v[34:35], v[34:35], v[136:137] neg_lo:[0,1] neg_hi:[0,1]
	v_cvt_pk_bf16_f32 v107, v36, v37
	v_lshlrev_b32_e32 v138, 16, v107
	v_and_b32_e32 v139, 0xffff0000, v107
	v_pk_add_f32 v[36:37], v[36:37], v[138:139] neg_lo:[0,1] neg_hi:[0,1]
	s_nop 0
	v_cvt_pk_bf16_f32 v103, v36, v37
	v_cvt_pk_bf16_f32 v102, v34, v35
	v_cvt_pk_bf16_f32 v101, v32, v33
	v_cvt_pk_bf16_f32 v100, v30, v31
.LBB0_486:
	s_or_b64 exec, exec, s[36:37]
	s_cmp_lg_u32 s98, 0
	s_cbranch_scc1 .Lp2_nowait1
	s_waitcnt vmcnt(0)
	v_mov_b32_e32 v140, v20
	v_mov_b32_e32 v141, v21
	v_mov_b32_e32 v142, v22
	v_mov_b32_e32 v143, v23
	v_mov_b32_e32 v144, v24
	v_mov_b32_e32 v145, v25
	v_mov_b32_e32 v146, v26
	v_mov_b32_e32 v147, v27
	v_mov_b32_e32 v148, v28
	v_mov_b32_e32 v252, v28
	v_mov_b32_e32 v253, v28
	v_mov_b32_e32 v254, v28
	v_mov_b32_e32 v255, v28
.Lp2_nowait1:
	s_and_b32 s98, s38, 0xff
	s_cselect_b32 s98, 0, 1
	s_nop 1
	v_mfma_f32_16x16x32_bf16 v[32:35], v[100:103], v[140:143], v[252:255]
	v_mfma_f32_16x16x32_bf16 v[32:35], v[104:107], v[144:147], v[32:35]
	v_mfma_f32_16x16x32_bf16 v[32:35], v[104:107], v[140:143], v[32:35]
	s_nop 7
	v_min_f32_e32 v36, 0, v32
	v_mul_f32_e64 v32, |v32|, s89
	v_exp_f32_e32 v32, v32
	v_mul_f32_e64 v37, |v33|, s89
	v_exp_f32_e32 v37, v37
	v_add_f32_e32 v32, 1.0, v32
	v_add_f32_e32 v37, 1.0, v37
	v_log_f32_e32 v32, v32
	v_log_f32_e32 v37, v37
	v_mul_f32_e32 v39, 0x3d800000, v32
	v_min_f32_e32 v33, 0, v33
	v_fma_f32 v32, v36, s93, -v39
	v_mul_f32_e32 v36, 0x3d800000, v37
	v_mul_f32_e64 v37, |v34|, s89
	v_exp_f32_e32 v37, v37
	v_fma_f32 v33, v33, s93, -v36
	v_add_f32_e32 v36, 1.0, v37
	s_nop 1
	v_log_f32_e32 v36, v36
	v_add_f32_e32 v37, v33, v32
	v_min_f32_e32 v33, 0, v34
	v_mul_f32_e32 v34, 0x3d800000, v36
	s_nop 0
	v_mul_f32_e64 v36, |v35|, s89
	v_exp_f32_e32 v36, v36
	v_fma_f32 v33, v33, s93, -v34
	v_add_u32_e32 v38, 0x8800, v98
	v_add_f32_e32 v34, 1.0, v36
	s_nop 1
	v_log_f32_e32 v34, v34
	v_add_f32_e32 v36, v33, v37
	v_min_f32_e32 v33, 0, v35
	v_mul_f32_e32 v35, 0x3d800000, v34
	s_nop 1
	v_fma_f32 v33, v33, s93, -v35
	v_add_f32_e32 v34, v33, v36
	ds_bpermute_b32 v33, v83, v34
	s_waitcnt lgkmcnt(0)
	v_cndmask_b32_e64 v33, v33, 0, s[8:9]
	v_add_f32_e32 v33, v33, v34
	ds_bpermute_b32 v35, v84, v33
	s_waitcnt lgkmcnt(0)
	v_cndmask_b32_e64 v35, 0, v35, s[10:11]
	v_add_f32_e32 v33, v35, v33
	v_sub_f32_e32 v35, v33, v34
	ds_bpermute_b32 v33, v85, v33
	v_add_f32_e32 v35, 0, v35
	v_add_f32_e32 v32, v32, v35
	v_add_f32_e32 v37, v37, v35
	ds_write2_b32 v38, v32, v37 offset1:132
	v_add_f32_e32 v32, v36, v35
	v_add_f32_e32 v34, v34, v35
	v_add_u32_e32 v35, 0x8c00, v98
	ds_write2_b32 v35, v32, v34 offset0:8 offset1:140
	v_mov_b32_e32 v108, 0
	v_mov_b32_e32 v109, 0
	v_mov_b32_e32 v110, 0
	v_mov_b32_e32 v111, 0
	v_mov_b32_e32 v112, 0
	v_mov_b32_e32 v113, 0
	v_mov_b32_e32 v114, 0
	v_mov_b32_e32 v115, 0
	s_and_saveexec_b64 s[36:37], s[6:7]
	s_cbranch_execz .LBB0_488
	ds_read_b128 v[34:37], v96 offset:1024
	ds_read_b128 v[38:41], v96 offset:1040
	s_waitcnt lgkmcnt(1)
	v_cvt_pk_bf16_f32 v112, v34, v35
	v_lshlrev_b32_e32 v132, 16, v112
	v_and_b32_e32 v133, 0xffff0000, v112
	v_pk_add_f32 v[34:35], v[34:35], v[132:133] neg_lo:[0,1] neg_hi:[0,1]
	v_cvt_pk_bf16_f32 v113, v36, v37
	v_lshlrev_b32_e32 v134, 16, v113
	v_and_b32_e32 v135, 0xffff0000, v113
	v_pk_add_f32 v[36:37], v[36:37], v[134:135] neg_lo:[0,1] neg_hi:[0,1]
	s_waitcnt lgkmcnt(0)
	v_cvt_pk_bf16_f32 v114, v38, v39
	v_lshlrev_b32_e32 v136, 16, v114
	v_and_b32_e32 v137, 0xffff0000, v114
	v_pk_add_f32 v[38:39], v[38:39], v[136:137] neg_lo:[0,1] neg_hi:[0,1]
	v_cvt_pk_bf16_f32 v115, v40, v41
	v_lshlrev_b32_e32 v138, 16, v115
	v_and_b32_e32 v139, 0xffff0000, v115
	v_pk_add_f32 v[40:41], v[40:41], v[138:139] neg_lo:[0,1] neg_hi:[0,1]
	s_nop 0
	v_cvt_pk_bf16_f32 v111, v40, v41
	v_cvt_pk_bf16_f32 v110, v38, v39
	v_cvt_pk_bf16_f32 v109, v36, v37
	v_cvt_pk_bf16_f32 v108, v34, v35
; #define LAS __attribute__((address_space(3)))
; __device__ __forceinline__ void phase_gla_pre(const Params& P, LAS unsigned char* lds, bool dry) {
;     ...
;         for (int tt = 0; tt < 4; ++tt) {
;             bf16x8 ahi = (bf16x8){0, 0, 0, 0, 0, 0, 0, 0}, alo = ahi;
;             if (g < 2) { const f32x4 l0 = *(const LAS f32x4*)(Llr + (16 * tt + fr) * 16 + 8 * g), l1 = *(const LAS f32x4*)(Llr + (16 * tt + fr) * 16 + 8 * g + 4); split8(l0, l1, ahi, alo); }
;             f32x4 acc = (f32x4){bg, bg, bg, bg};
;             acc = __builtin_amdgcn_mfma_f32_16x16x32_bf16(alo, bhi, acc, 0, 0, 0); acc = __builtin_amdgcn_mfma_f32_16x16x32_bf16(ahi, blo, acc, 0, 0, 0); acc = __builtin_amdgcn_mfma_f32_16x16x32_bf16(ahi, bhi, acc, 0, 0, 0);
;             float pr[4];
; #pragma unroll
;             for (int r = 0; r < 4; ++r) { const float lg = acc[r]; const float ls = fminf(lg, 0.f) - __logf(1.0f + __expf(-fabsf(lg))); pr[r] = ls * (1.0f / 16.0f) + (r ? pr[r - 1] : 0.f); }
;             const float T = pr[3];
;             const float u1 = __shfl_up(T, 16), s1 = T + (g >= 1 ? u1 : 0.f);
;             const float u2 = __shfl_up(s1, 32), s2 = s1 + (g >= 2 ? u2 : 0.f);
;             const float base = run + (s2 - T); run += __shfl(s2, 48 + fr);
; #pragma unroll
;             for (int r = 0; r < 4; ++r) *(LAS float*)(Lb + (16 * tt + 4 * g + r) * BP + (16 * w + fr) * 4) = base + pr[r];
.LBB0_488:
	s_or_b64 exec, exec, s[36:37]
	s_nop 0
	v_mfma_f32_16x16x32_bf16 v[34:37], v[108:111], v[140:143], v[252:255]
	v_mfma_f32_16x16x32_bf16 v[34:37], v[112:115], v[144:147], v[34:37]
	v_mfma_f32_16x16x32_bf16 v[34:37], v[112:115], v[140:143], v[34:37]
	s_nop 7
	v_min_f32_e32 v38, 0, v34
	v_mul_f32_e64 v34, |v34|, s89
	v_exp_f32_e32 v34, v34
	v_mul_f32_e64 v39, |v35|, s89
	v_exp_f32_e32 v39, v39
	v_add_f32_e32 v34, 1.0, v34
	v_add_f32_e32 v39, 1.0, v39
	v_log_f32_e32 v34, v34
	v_log_f32_e32 v39, v39
	v_mul_f32_e32 v41, 0x3d800000, v34
	v_fma_f32 v34, v38, s93, -v41
	v_mul_f32_e32 v38, 0x3d800000, v39
	v_min_f32_e32 v35, 0, v35
	v_mul_f32_e64 v39, |v36|, s89
	v_exp_f32_e32 v39, v39
	v_fma_f32 v35, v35, s93, -v38
	v_add_f32_e32 v38, 1.0, v39
	v_min_f32_e32 v36, 0, v36
	v_log_f32_e32 v38, v38
	v_add_f32_e32 v35, v35, v34
	v_mul_f32_e32 v39, 0x3d800000, v38
	s_nop 1
	v_mov_b32_e32 v38, v39
	v_mul_f32_e64 v39, |v37|, s89
	v_exp_f32_e32 v39, v39
	v_fma_f32 v36, v36, s93, -v38
	v_add_f32_e32 v38, 1.0, v39
	v_min_f32_e32 v37, 0, v37
	v_add_f32_e32 v36, v36, v35
	v_log_f32_e32 v38, v38
	s_waitcnt lgkmcnt(2)
	v_add_f32_e32 v40, 0, v33
	v_mul_f32_e32 v39, 0x3d800000, v38
	s_nop 1
	v_fma_f32 v37, v37, s93, -v39
	v_add_f32_e32 v37, v37, v36
	ds_bpermute_b32 v38, v83, v37
	s_waitcnt lgkmcnt(0)
	v_cndmask_b32_e64 v38, v38, 0, s[8:9]
	v_add_f32_e32 v38, v38, v37
	ds_bpermute_b32 v39, v84, v38
	s_waitcnt lgkmcnt(0)
	v_cndmask_b32_e64 v33, 0, v39, s[10:11]
	v_add_f32_e32 v33, v33, v38
	v_sub_f32_e32 v38, v33, v37
	ds_bpermute_b32 v41, v85, v33
	v_add_f32_e32 v38, v40, v38
	v_add_f32_e32 v33, v34, v38
	v_add_f32_e32 v34, v35, v38
	v_add_u32_e32 v35, 0xa800, v98
	ds_write2_b32 v35, v33, v34 offset0:64 offset1:196
	v_add_f32_e32 v33, v36, v38
	v_add_f32_e32 v34, v37, v38
	v_add_u32_e32 v35, 0xac00, v98
	ds_write2_b32 v35, v33, v34 offset0:72 offset1:204
	v_mov_b32_e32 v116, 0
	v_mov_b32_e32 v117, 0
	v_mov_b32_e32 v118, 0
	v_mov_b32_e32 v119, 0
	v_mov_b32_e32 v120, 0
	v_mov_b32_e32 v121, 0
	v_mov_b32_e32 v122, 0
	v_mov_b32_e32 v123, 0
	s_and_saveexec_b64 s[36:37], s[6:7]
	s_cbranch_execz .LBB0_490
	ds_read_b128 v[32:35], v96 offset:2048
	ds_read_b128 v[36:39], v96 offset:2064
	s_waitcnt lgkmcnt(1)
	v_cvt_pk_bf16_f32 v120, v32, v33
	v_lshlrev_b32_e32 v132, 16, v120
	v_and_b32_e32 v133, 0xffff0000, v120
	v_pk_add_f32 v[32:33], v[32:33], v[132:133] neg_lo:[0,1] neg_hi:[0,1]
	v_cvt_pk_bf16_f32 v121, v34, v35
	v_lshlrev_b32_e32 v134, 16, v121
	v_and_b32_e32 v135, 0xffff0000, v121
	v_pk_add_f32 v[34:35], v[34:35], v[134:135] neg_lo:[0,1] neg_hi:[0,1]
	s_waitcnt lgkmcnt(0)
	v_cvt_pk_bf16_f32 v122, v36, v37
	v_lshlrev_b32_e32 v136, 16, v122
	v_and_b32_e32 v137, 0xffff0000, v122
	v_pk_add_f32 v[36:37], v[36:37], v[136:137] neg_lo:[0,1] neg_hi:[0,1]
	v_cvt_pk_bf16_f32 v123, v38, v39
	v_lshlrev_b32_e32 v138, 16, v123
	v_and_b32_e32 v139, 0xffff0000, v123
	v_pk_add_f32 v[38:39], v[38:39], v[138:139] neg_lo:[0,1] neg_hi:[0,1]
	s_nop 0
	v_cvt_pk_bf16_f32 v119, v38, v39
	v_cvt_pk_bf16_f32 v118, v36, v37
	v_cvt_pk_bf16_f32 v117, v34, v35
	v_cvt_pk_bf16_f32 v116, v32, v33
.LBB0_490:
	s_or_b64 exec, exec, s[36:37]
	s_nop 0
	v_mfma_f32_16x16x32_bf16 v[32:35], v[116:119], v[140:143], v[252:255]
	s_waitcnt lgkmcnt(2)
	v_add_f32_e32 v40, v40, v41
	v_mfma_f32_16x16x32_bf16 v[32:35], v[120:123], v[144:147], v[32:35]
	v_mfma_f32_16x16x32_bf16 v[32:35], v[120:123], v[140:143], v[32:35]
	s_nop 7
	v_min_f32_e32 v36, 0, v32
	v_mul_f32_e64 v32, |v32|, s89
	v_exp_f32_e32 v32, v32
	v_mul_f32_e64 v37, |v33|, s89
	v_exp_f32_e32 v37, v37
	v_add_f32_e32 v32, 1.0, v32
	v_add_f32_e32 v37, 1.0, v37
	v_log_f32_e32 v32, v32
	v_log_f32_e32 v37, v37
	v_mul_f32_e32 v39, 0x3d800000, v32
	v_fma_f32 v32, v36, s93, -v39
	v_mul_f32_e32 v36, 0x3d800000, v37
	v_min_f32_e32 v33, 0, v33
	v_mul_f32_e64 v37, |v34|, s89
	v_exp_f32_e32 v37, v37
	v_fma_f32 v33, v33, s93, -v36
	v_add_f32_e32 v36, 1.0, v37
	v_min_f32_e32 v34, 0, v34
	v_log_f32_e32 v36, v36
	v_add_f32_e32 v33, v33, v32
	v_mul_f32_e32 v37, 0x3d800000, v36
	s_nop 1
	v_mov_b32_e32 v36, v37
	v_mul_f32_e64 v37, |v35|, s89
	v_exp_f32_e32 v37, v37
	v_fma_f32 v34, v34, s93, -v36
	v_add_f32_e32 v36, 1.0, v37
	v_min_f32_e32 v35, 0, v35
	v_add_f32_e32 v34, v34, v33
	v_log_f32_e32 v36, v36
	s_nop 0
	v_mul_f32_e32 v37, 0x3d800000, v36
	s_nop 1
	v_fma_f32 v35, v35, s93, -v37
	v_add_f32_e32 v35, v35, v34
	ds_bpermute_b32 v36, v83, v35
	s_waitcnt lgkmcnt(0)
	v_cndmask_b32_e64 v36, v36, 0, s[8:9]
	v_add_f32_e32 v36, v36, v35
	ds_bpermute_b32 v37, v84, v36
	s_waitcnt lgkmcnt(0)
	v_cndmask_b32_e64 v37, 0, v37, s[10:11]
	v_add_f32_e32 v36, v37, v36
	v_sub_f32_e32 v37, v36, v35
	ds_bpermute_b32 v41, v85, v36
	v_add_f32_e32 v37, v40, v37
	v_add_f32_e32 v32, v32, v37
	v_add_f32_e32 v33, v33, v37
	v_add_u32_e32 v36, 0xca00, v98
	ds_write2_b32 v36, v32, v33 offset1:132
	v_add_f32_e32 v32, v34, v37
	v_add_f32_e32 v33, v35, v37
	v_add_u32_e32 v34, 0xce00, v98
	ds_write2_b32 v34, v32, v33 offset0:8 offset1:140
	v_mov_b32_e32 v124, 0
	v_mov_b32_e32 v125, 0
	v_mov_b32_e32 v126, 0
	v_mov_b32_e32 v127, 0
	v_mov_b32_e32 v128, 0
	v_mov_b32_e32 v129, 0
	v_mov_b32_e32 v130, 0
	v_mov_b32_e32 v131, 0
	s_and_saveexec_b64 s[36:37], s[6:7]
	s_cbranch_execz .LBB0_492
	ds_read_b128 v[32:35], v96 offset:3072
	ds_read_b128 v[36:39], v96 offset:3088
	s_waitcnt lgkmcnt(1)
	v_cvt_pk_bf16_f32 v128, v32, v33
	v_lshlrev_b32_e32 v132, 16, v128
	v_and_b32_e32 v133, 0xffff0000, v128
	v_pk_add_f32 v[32:33], v[32:33], v[132:133] neg_lo:[0,1] neg_hi:[0,1]
	v_cvt_pk_bf16_f32 v129, v34, v35
	v_lshlrev_b32_e32 v134, 16, v129
	v_and_b32_e32 v135, 0xffff0000, v129
	v_pk_add_f32 v[34:35], v[34:35], v[134:135] neg_lo:[0,1] neg_hi:[0,1]
	s_waitcnt lgkmcnt(0)
	v_cvt_pk_bf16_f32 v130, v36, v37
	v_lshlrev_b32_e32 v136, 16, v130
	v_and_b32_e32 v137, 0xffff0000, v130
	v_pk_add_f32 v[36:37], v[36:37], v[136:137] neg_lo:[0,1] neg_hi:[0,1]
	v_cvt_pk_bf16_f32 v131, v38, v39
	v_lshlrev_b32_e32 v138, 16, v131
	v_and_b32_e32 v139, 0xffff0000, v131
	v_pk_add_f32 v[38:39], v[38:39], v[138:139] neg_lo:[0,1] neg_hi:[0,1]
	s_nop 0
	v_cvt_pk_bf16_f32 v127, v38, v39
	v_cvt_pk_bf16_f32 v126, v36, v37
	v_cvt_pk_bf16_f32 v125, v34, v35
	v_cvt_pk_bf16_f32 v124, v32, v33
; #define LAS __attribute__((address_space(3)))
; __device__ __forceinline__ void phase_gla_pre(const Params& P, LAS unsigned char* lds, bool dry) {
;     ...
;         for (int tt = 0; tt < 4; ++tt) {
;             bf16x8 ahi = (bf16x8){0, 0, 0, 0, 0, 0, 0, 0}, alo = ahi;
;             if (g < 2) { const f32x4 l0 = *(const LAS f32x4*)(Llr + (16 * tt + fr) * 16 + 8 * g), l1 = *(const LAS f32x4*)(Llr + (16 * tt + fr) * 16 + 8 * g + 4); split8(l0, l1, ahi, alo); }
;             f32x4 acc = (f32x4){bg, bg, bg, bg};
;             acc = __builtin_amdgcn_mfma_f32_16x16x32_bf16(alo, bhi, acc, 0, 0, 0); acc = __builtin_amdgcn_mfma_f32_16x16x32_bf16(ahi, blo, acc, 0, 0, 0); acc = __builtin_amdgcn_mfma_f32_16x16x32_bf16(ahi, bhi, acc, 0, 0, 0);
;             float pr[4];
; #pragma unroll
;             for (int r = 0; r < 4; ++r) { const float lg = acc[r]; const float ls = fminf(lg, 0.f) - __logf(1.0f + __expf(-fabsf(lg))); pr[r] = ls * (1.0f / 16.0f) + (r ? pr[r - 1] : 0.f); }
;             const float T = pr[3];
;             const float u1 = __shfl_up(T, 16), s1 = T + (g >= 1 ? u1 : 0.f);
;             const float u2 = __shfl_up(s1, 32), s2 = s1 + (g >= 2 ? u2 : 0.f);
;             const float base = run + (s2 - T); run += __shfl(s2, 48 + fr);
; #pragma unroll
;             for (int r = 0; r < 4; ++r) *(LAS float*)(Lb + (16 * tt + 4 * g + r) * BP + (16 * w + fr) * 4) = base + pr[r];
;         }
;         __syncthreads();
;         {
;             f32x4 bb[4], bm[4], bl[4];
; #pragma unroll
;             for (int i = 0; i < 4; ++i) { bb[i] = *(const LAS f32x4*)(Lb + te * BP + (16 * kc + 4 * i) * 4); bm[i] = *(const LAS f32x4*)(Lb + 31 * BP + (16 * kc + 4 * i) * 4); bl[i] = *(const LAS f32x4*)(Lb + 63 * BP + (16 * kc + 4 * i) * 4); }
;             unsigned oqi[8], oki[8], oqd[8], oks[8];
; #pragma unroll
;             for (int e2 = 0; e2 < 8; ++e2) {
;                 const unsigned qw = e2 < 4 ? rq[0][e2] : rq[1][e2 - 4], kw = e2 < 4 ? rk[0][e2] : rk[1][e2 - 4];
;                 float vqi[2], vki[2], vqd[2], vks[2];
; #pragma unroll
;                 for (int hh = 0; hh < 2; ++hh) {
;                     const int e = 2 * e2 + hh; const float bv = bb[e >> 2][e & 3], bmv = bm[e >> 2][e & 3], blv = bl[e >> 2][e & 3];
;                     const float qv = hh ? bfhi(qw) : bflo(qw), kv = hh ? bfhi(kw) : bflo(kw);
;                     const float e1 = __expf(bv - bmv);
.LBB0_492:
	s_or_b64 exec, exec, s[36:37]
	s_nop 0
	v_mfma_f32_16x16x32_bf16 v[28:31], v[124:127], v[140:143], v[252:255]
	v_and_b32_e32 v111, 0xffff0000, v5
	v_and_b32_e32 v110, 0xffff0000, v4
	v_and_b32_e32 v117, 0xffff0000, v13
	v_mfma_f32_16x16x32_bf16 v[24:27], v[128:131], v[144:147], v[28:31]
	v_and_b32_e32 v116, 0xffff0000, v12
	v_and_b32_e32 v121, 0xffff0000, v7
	v_and_b32_e32 v120, 0xffff0000, v6
	v_mfma_f32_16x16x32_bf16 v[20:23], v[128:131], v[140:143], v[24:27]
	v_and_b32_e32 v127, 0xffff0000, v17
	v_and_b32_e32 v126, 0xffff0000, v16
	v_lshlrev_b32_e32 v125, 16, v17
	v_lshlrev_b32_e32 v124, 16, v16
	v_lshlrev_b32_e32 v133, 16, v11
	s_nop 2
	v_min_f32_e32 v24, 0, v20
	v_mul_f32_e64 v20, |v20|, s89
	v_exp_f32_e32 v20, v20
	v_mul_f32_e64 v25, |v21|, s89
	v_exp_f32_e32 v25, v25
	v_add_f32_e32 v20, 1.0, v20
	v_add_f32_e32 v25, 1.0, v25
	v_log_f32_e32 v20, v20
	v_log_f32_e32 v25, v25
	v_mul_f32_e32 v27, 0x3d800000, v20
	v_fma_f32 v20, v24, s93, -v27
	v_mul_f32_e32 v24, 0x3d800000, v25
	v_min_f32_e32 v21, 0, v21
	v_mul_f32_e64 v25, |v22|, s89
	v_exp_f32_e32 v25, v25
	v_fma_f32 v21, v21, s93, -v24
	v_add_f32_e32 v24, 1.0, v25
	v_min_f32_e32 v22, 0, v22
	v_log_f32_e32 v24, v24
	v_add_f32_e32 v21, v21, v20
	v_lshlrev_b32_e32 v132, 16, v10
	v_mul_f32_e32 v25, 0x3d800000, v24
	v_and_b32_e32 v135, 0xffff0000, v11
	v_and_b32_e32 v134, 0xffff0000, v10
	v_mov_b32_e32 v24, v25
	v_mul_f32_e64 v25, |v23|, s89
	v_exp_f32_e32 v25, v25
	v_fma_f32 v22, v22, s93, -v24
	v_add_f32_e32 v24, 1.0, v25
	v_min_f32_e32 v23, 0, v23
	v_add_f32_e32 v22, v22, v21
	v_log_f32_e32 v24, v24
	s_waitcnt lgkmcnt(2)
	v_add_f32_e32 v26, v40, v41
	s_and_b32 s74, s1, 0xfc0
	s_ashr_i32 s83, s82, 31
	v_mul_f32_e32 v25, 0x3d800000, v24
	s_nop 1
	v_fma_f32 v23, v23, s93, -v25
	v_add_f32_e32 v23, v23, v22
	ds_bpermute_b32 v24, v83, v23
	s_lshl_b64 s[36:37], s[82:83], 20
	s_waitcnt lgkmcnt(0)
	v_cndmask_b32_e64 v24, v24, 0, s[8:9]
	v_add_f32_e32 v24, v24, v23
	ds_bpermute_b32 v25, v84, v24
	s_waitcnt lgkmcnt(0)
	v_cndmask_b32_e64 v25, 0, v25, s[10:11]
	v_add_f32_e32 v24, v25, v24
	v_sub_f32_e32 v24, v24, v23
	v_add_f32_e32 v24, v26, v24
	v_add_f32_e32 v20, v20, v24
	v_add_f32_e32 v21, v21, v24
	v_add_u32_e32 v25, 0xea00, v98
	ds_write2_b32 v25, v20, v21 offset0:64 offset1:196
	v_add_f32_e32 v20, v22, v24
	v_add_f32_e32 v21, v23, v24
	v_add_u32_e32 v22, 0xee00, v98
	ds_write2_b32 v22, v20, v21 offset0:72 offset1:204
	v_add_u32_e32 v22, s94, v87
	s_waitcnt lgkmcnt(0)
	s_barrier
	v_add_u32_e32 v20, v86, v87
	v_add_u32_e32 v21, 0, v87
	ds_read_b128 v[32:35], v22
	ds_read_b128 v[24:27], v89
	ds_read_b128 v[60:63], v21 offset:51184
	ds_read_b128 v[64:67], v20 offset:34816
	ds_read_b128 v[74:77], v20 offset:34832
	ds_read_b128 v[44:47], v20 offset:34848
	ds_read_b128 v[36:39], v20 offset:34864
	ds_read_b128 v[100:103], v21 offset:51200
	s_waitcnt lgkmcnt(4)
	v_sub_f32_e32 v61, v65, v61
	v_sub_f32_e32 v63, v67, v63
	v_exp_f32_e32 v72, v61
	v_sub_f32_e32 v61, v32, v64
	v_exp_f32_e32 v73, v63
	v_exp_f32_e32 v78, v61
	v_sub_f32_e32 v20, v64, v60
	v_exp_f32_e32 v108, v65
	v_sub_f32_e32 v61, v66, v62
	v_sub_f32_e32 v62, v33, v65
	v_sub_f32_e32 v63, v34, v66
	v_exp_f32_e32 v60, v20
	v_exp_f32_e32 v70, v64
	v_rcp_f32_e32 v64, v72
	v_exp_f32_e32 v61, v61
	v_exp_f32_e32 v71, v66
	v_rcp_f32_e32 v65, v73
	v_exp_f32_e32 v79, v63
	v_exp_f32_e32 v109, v67
	v_sub_f32_e32 v63, v35, v67
	v_lshlrev_b32_e32 v67, 16, v5
	v_lshlrev_b32_e32 v66, 16, v4
	v_pk_mul_f32 v[112:113], v[60:61], v[66:67]
	v_pk_mul_f32 v[114:115], v[72:73], v[110:111]
	v_pk_mul_f32 v[72:73], v[64:65], v[116:117]
	v_pk_mul_f32 v[64:65], v[70:71], v[66:67]
	s_waitcnt lgkmcnt(0)
	v_sub_f32_e32 v66, v74, v100
	v_exp_f32_e32 v70, v66
	v_pk_mul_f32 v[66:67], v[108:109], v[110:111]
	v_exp_f32_e32 v108, v74
	v_sub_f32_e32 v71, v75, v101
	v_exp_f32_e32 v100, v71
	v_sub_f32_e32 v71, v24, v74
	v_exp_f32_e32 v62, v62
	v_exp_f32_e32 v63, v63
	v_exp_f32_e32 v74, v71
	v_mov_b32_e32 v71, v75
	v_sub_f32_e32 v75, v25, v75
	v_exp_f32_e32 v118, v75
	v_pk_mul_f32 v[62:63], v[62:63], v[116:117]
	v_exp_f32_e32 v116, v71
	v_sub_f32_e32 v71, v76, v102
	v_exp_f32_e32 v109, v76
	v_sub_f32_e32 v75, v77, v103
	v_rcp_f32_e32 v68, v60
	v_rcp_f32_e32 v69, v61
	v_exp_f32_e32 v71, v71
	v_exp_f32_e32 v101, v75
	v_sub_f32_e32 v75, v26, v76
	v_exp_f32_e32 v117, v77
	v_sub_f32_e32 v76, v27, v77
	v_lshlrev_b32_e32 v61, 16, v13
	v_lshlrev_b32_e32 v60, 16, v12
	v_exp_f32_e32 v119, v76
	v_lshlrev_b32_e32 v77, 16, v7
	v_lshlrev_b32_e32 v76, 16, v6
	v_pk_mul_f32 v[68:69], v[68:69], v[60:61]
	v_pk_mul_f32 v[60:61], v[78:79], v[60:61]
	v_rcp_f32_e32 v78, v70
	v_rcp_f32_e32 v110, v100
	v_rcp_f32_e32 v79, v71
	v_rcp_f32_e32 v111, v101
	v_pk_mul_f32 v[70:71], v[70:71], v[76:77]
	v_pk_mul_f32 v[100:101], v[100:101], v[120:121]
	v_cvt_pk_bf16_f32 v224, v112, v114
	v_cvt_pk_bf16_f32 v222, v113, v115
	v_cvt_pk_bf16_f32 v102, v70, v100
	v_cvt_pk_bf16_f32 v103, v71, v101
	ds_read_b128 v[104:107], v21 offset:51216
	ds_read_b128 v[40:43], v21 offset:51232
	ds_read_b128 v[28:31], v90
	ds_read_b128 v[20:23], v91
	v_lshlrev_b32_e32 v71, 16, v15
	v_lshlrev_b32_e32 v70, 16, v14
	v_mov_b32_e32 v101, v222
	v_mov_b32_e32 v100, v224
	v_pk_mul_f32 v[114:115], v[78:79], v[70:71]
	s_waitcnt lgkmcnt(3)
; __device__ __forceinline__ void phase_gla_pre(const Params& P, LAS unsigned char* lds, bool dry) {
;     ...
;             f32x4 bb[4], bm[4], bl[4];
; #pragma unroll
;             for (int i = 0; i < 4; ++i) { bb[i] = *(const LAS f32x4*)(Lb + te * BP + (16 * kc + 4 * i) * 4); bm[i] = *(const LAS f32x4*)(Lb + 31 * BP + (16 * kc + 4 * i) * 4); bl[i] = *(const LAS f32x4*)(Lb + 63 * BP + (16 * kc + 4 * i) * 4); }
;             unsigned oqi[8], oki[8], oqd[8], oks[8];
; #pragma unroll
;             for (int e2 = 0; e2 < 8; ++e2) {
;                 const unsigned qw = e2 < 4 ? rq[0][e2] : rq[1][e2 - 4], kw = e2 < 4 ? rk[0][e2] : rk[1][e2 - 4];
;                 float vqi[2], vki[2], vqd[2], vks[2];
; #pragma unroll
;                 for (int hh = 0; hh < 2; ++hh) {
;                     const int e = 2 * e2 + hh; const float bv = bb[e >> 2][e & 3], bmv = bm[e >> 2][e & 3], blv = bl[e >> 2][e & 3];
;                     const float qv = hh ? bfhi(qw) : bflo(qw), kv = hh ? bfhi(kw) : bflo(kw);
;                     const float e1 = __expf(bv - bmv);
;                     vqi[hh] = qv * e1; vki[hh] = kv * __builtin_amdgcn_rcpf(e1); vqd[hh] = qv * __expf(bv); vks[hh] = kv * __expf(blv - bv);
;                 }
;                 oqi[e2] = pk2(vqi[0], vqi[1]); oki[e2] = pk2(vki[0], vki[1]); oqd[e2] = pk2(vqd[0], vqd[1]); oks[e2] = pk2(vks[0], vks[1]);
;             }
;             *(LAS u32x4*)(Lqi + te * QP + 32 * kc) = (u32x4){oqi[0], oqi[1], oqi[2], oqi[3]}; *(LAS u32x4*)(Lqi + te * QP + 32 * kc + 16) = (u32x4){oqi[4], oqi[5], oqi[6], oqi[7]};
;             *(LAS u32x4*)(Lki + te * QP + 32 * kc) = (u32x4){oki[0], oki[1], oki[2], oki[3]}; *(LAS u32x4*)(Lki + te * QP + 32 * kc + 16) = (u32x4){oki[4], oki[5], oki[6], oki[7]};
;             if (!dry) {
;                 bf16_t* p_ = PJ + ((size_t)bh * SEQ + c * 64 + te) * 128 + 16 * kc;
;                 *(u32x4*)(p_ + T_Q) = (u32x4){oqd[0], oqd[1], oqd[2], oqd[3]}; *(u32x4*)(p_ + T_Q + 8) = (u32x4){oqd[4], oqd[5], oqd[6], oqd[7]};
;                 *(u32x4*)(p_ + T_K) = (u32x4){oks[0], oks[1], oks[2], oks[3]}; *(u32x4*)(p_ + T_K + 8) = (u32x4){oks[4], oks[5], oks[6], oks[7]};
;                 if (te == 63) {
; #pragma unroll
;                     for (int i = 0; i < 4; ++i) *(f32x4*)(DEC + (size_t)item * 128 + 16 * kc + 4 * i) = (f32x4){__expf(bl[i][0]), __expf(bl[i][1]), __expf(bl[i][2]), __expf(bl[i][3])};
	v_sub_f32_e32 v78, v44, v104
	v_sub_f32_e32 v105, v45, v105
	v_exp_f32_e32 v75, v75
	v_exp_f32_e32 v104, v78
	v_pk_mul_f32 v[78:79], v[116:117], v[120:121]
	v_exp_f32_e32 v116, v105
	v_mov_b32_e32 v105, v45
	s_waitcnt lgkmcnt(1)
	v_sub_f32_e32 v45, v29, v45
	v_and_b32_e32 v113, 0xffff0000, v15
	v_and_b32_e32 v112, 0xffff0000, v14
	v_exp_f32_e32 v120, v105
	v_sub_f32_e32 v105, v46, v106
	v_exp_f32_e32 v106, v45
	v_pk_mul_f32 v[110:111], v[110:111], v[112:113]
	v_pk_mul_f32 v[70:71], v[74:75], v[70:71]
	v_pk_mul_f32 v[74:75], v[118:119], v[112:113]
	v_exp_f32_e32 v113, v46
	v_sub_f32_e32 v45, v47, v107
	v_exp_f32_e32 v117, v45
	v_sub_f32_e32 v45, v30, v46
	v_exp_f32_e32 v121, v47
	v_sub_f32_e32 v46, v31, v47
	v_pk_mul_f32 v[76:77], v[108:109], v[76:77]
	v_exp_f32_e32 v112, v44
	v_exp_f32_e32 v105, v105
	v_exp_f32_e32 v107, v46
	v_rcp_f32_e32 v118, v116
	v_rcp_f32_e32 v119, v117
	v_sub_f32_e32 v44, v28, v44
	v_lshlrev_b32_e32 v47, 16, v9
	v_lshlrev_b32_e32 v46, 16, v8
	v_rcp_f32_e32 v108, v104
	v_rcp_f32_e32 v109, v105
	v_pk_mul_f32 v[104:105], v[104:105], v[46:47]
	v_pk_mul_f32 v[112:113], v[112:113], v[46:47]
	v_sub_f32_e32 v40, v36, v40
	v_pk_mul_f32 v[46:47], v[106:107], v[126:127]
	v_mov_b32_e32 v107, v36
	s_waitcnt lgkmcnt(0)
	v_sub_f32_e32 v36, v20, v36
	v_exp_f32_e32 v44, v44
	v_exp_f32_e32 v45, v45
	v_pk_mul_f32 v[118:119], v[118:119], v[126:127]
	v_exp_f32_e32 v126, v36
	v_sub_f32_e32 v41, v37, v41
	v_exp_f32_e32 v130, v37
	v_sub_f32_e32 v36, v38, v42
	v_pk_mul_f32 v[108:109], v[108:109], v[124:125]
	v_pk_mul_f32 v[44:45], v[44:45], v[124:125]
	v_exp_f32_e32 v124, v41
	v_exp_f32_e32 v41, v36
	v_sub_f32_e32 v36, v21, v37
	v_and_b32_e32 v123, 0xffff0000, v9
	v_and_b32_e32 v122, 0xffff0000, v8
	v_exp_f32_e32 v42, v36
	v_pk_mul_f32 v[116:117], v[116:117], v[122:123]
	v_pk_mul_f32 v[120:121], v[120:121], v[122:123]
	v_exp_f32_e32 v123, v38
	v_sub_f32_e32 v36, v39, v43
	v_exp_f32_e32 v125, v36
	v_sub_f32_e32 v36, v22, v38
	v_exp_f32_e32 v40, v40
	v_exp_f32_e32 v127, v36
	v_exp_f32_e32 v131, v39
	v_sub_f32_e32 v36, v23, v39
	v_rcp_f32_e32 v128, v124
	v_rcp_f32_e32 v129, v125
	v_exp_f32_e32 v43, v36
	v_pk_mul_f32 v[36:37], v[40:41], v[132:133]
	v_pk_mul_f32 v[38:39], v[124:125], v[134:135]
	v_rcp_f32_e32 v106, v40
	v_exp_f32_e32 v122, v107
	v_rcp_f32_e32 v107, v41
	v_cvt_pk_bf16_f32 v228, v104, v116
	v_cvt_pk_bf16_f32 v227, v105, v117
	v_cvt_pk_bf16_f32 v38, v36, v38
	v_cvt_pk_bf16_f32 v39, v37, v39
	v_mov_b32_e32 v37, v227
	v_mov_b32_e32 v36, v228
	ds_write_b128 v92, v[100:103]
	ds_write_b128 v92, v[36:39] offset:16
	v_cvt_pk_bf16_f32 v36, v68, v72
	v_cvt_pk_bf16_f32 v37, v69, v73
	v_lshlrev_b32_e32 v41, 16, v19
	v_lshlrev_b32_e32 v40, 16, v18
	v_cvt_pk_bf16_f32 v39, v115, v111
	v_cvt_pk_bf16_f32 v38, v114, v110
	v_and_b32_e32 v105, 0xffff0000, v19
	v_and_b32_e32 v104, 0xffff0000, v18
	v_pk_mul_f32 v[106:107], v[106:107], v[40:41]
	ds_write_b128 v92, v[36:39] offset:17408
	v_pk_mul_f32 v[116:117], v[128:129], v[104:105]
	s_nop 0
	v_cvt_pk_bf16_f32 v39, v107, v117
	v_cvt_pk_bf16_f32 v38, v106, v116
	v_cvt_pk_bf16_f32 v37, v109, v119
	v_cvt_pk_bf16_f32 v36, v108, v118
	ds_write_b128 v92, v[36:39] offset:17424
	v_lshl_add_u64 v[36:37], s[74:75], 0, v[48:49]
	v_lshlrev_b64 v[36:37], 8, v[36:37]
	v_lshl_add_u64 v[38:39], v[52:53], 0, s[36:37]
	v_lshl_add_u64 v[68:69], v[38:39], 0, v[36:37]
	v_cvt_pk_bf16_f32 v36, v64, v66
	v_cvt_pk_bf16_f32 v37, v65, v67
	s_brev_b32 s36, 16
	v_cvt_pk_bf16_f32 v39, v77, v79
	v_add_co_u32_e32 v64, vcc, s36, v68
	v_cvt_pk_bf16_f32 v38, v76, v78
	s_nop 0
	v_addc_co_u32_e32 v65, vcc, 0, v69, vcc
	v_pk_mul_f32 v[122:123], v[122:123], v[132:133]
	global_store_dwordx4 v[64:65], v[36:39], off
	v_pk_mul_f32 v[124:125], v[130:131], v[134:135]
	s_nop 0
	v_cvt_pk_bf16_f32 v39, v123, v125
	v_cvt_pk_bf16_f32 v38, v122, v124
	v_cvt_pk_bf16_f32 v37, v113, v121
	v_cvt_pk_bf16_f32 v36, v112, v120
	global_store_dwordx4 v[64:65], v[36:39], off offset:16
	s_nop 1
	s_nop 0
	v_cvt_pk_bf16_f32 v36, v60, v62
	v_cvt_pk_bf16_f32 v37, v61, v63
	v_cvt_pk_bf16_f32 v39, v71, v75
	v_add_co_u32_e32 v60, vcc, s95, v68
	v_pk_mul_f32 v[42:43], v[42:43], v[104:105]
	v_cvt_pk_bf16_f32 v38, v70, v74
	v_addc_co_u32_e32 v61, vcc, 0, v69, vcc
	v_pk_mul_f32 v[40:41], v[126:127], v[40:41]
	global_store_dwordx4 v[60:61], v[36:39], off
	s_nop 1
	v_cvt_pk_bf16_f32 v36, v44, v46
	v_cvt_pk_bf16_f32 v37, v45, v47
	v_cvt_pk_bf16_f32 v38, v40, v42
	v_cvt_pk_bf16_f32 v39, v41, v43
	global_store_dwordx4 v[60:61], v[36:39], off offset:16
	s_and_saveexec_b64 s[36:37], s[12:13]
	s_cbranch_execz .LBB0_494
	v_exp_f32_e32 v32, v32
	v_exp_f32_e32 v33, v33
	v_exp_f32_e32 v34, v34
	v_exp_f32_e32 v35, v35
	s_ashr_i32 s81, s80, 31
	v_exp_f32_e32 v24, v24
	v_exp_f32_e32 v25, v25
	v_exp_f32_e32 v26, v26
	v_exp_f32_e32 v27, v27
	s_lshl_b64 s[42:43], s[80:81], 9
	v_exp_f32_e32 v28, v28
	v_exp_f32_e32 v29, v29
	v_exp_f32_e32 v30, v30
	v_exp_f32_e32 v31, v31
	v_lshl_add_u64 v[36:37], v[54:55], 0, s[42:43]
	v_exp_f32_e32 v20, v20
	v_exp_f32_e32 v21, v21
	v_exp_f32_e32 v22, v22
	v_exp_f32_e32 v23, v23
	global_store_dwordx4 v[36:37], v[32:35], off
	global_store_dwordx4 v[36:37], v[24:27], off offset:16
	global_store_dwordx4 v[36:37], v[28:31], off offset:32
	global_store_dwordx4 v[36:37], v[20:23], off offset:48
